# diff attention: per-tile max chain removed from the hot path; overflow check on the tile's probability sum after exp, rare path recomputes the tile's scores and takes the exact max-based rescale
# speedup vs baseline: 1.0125x; 1.0068x over previous
; #define ALAS __attribute__((address_space(3)))
; template <bool WIN> ...
;     ...
;             float ls0 = 0.f, ls1 = 0.f;
;     ...
;             union PFU { u32x4 u; bf16x8 b; };
;             PFU p0, p1, p2, p3;
;             AT_EXP(s0, 0, p0);
; #pragma unroll
;             for (int kk = 0; kk < 2; ++kk)
; #pragma unroll
;                 for (int db = 0; db < NDB; ++db) vc[kk * NDB + db] = *(const ALAS bf16x8*)(sb + vx[kk + 2] + db * 4096);
;             __builtin_amdgcn_sched_barrier(0);
; #pragma unroll
;             for (int db = 0; db < NDB; ++db) o[db] = __builtin_amdgcn_mfma_f32_32x32x16_bf16(va[db], p0.b, o[db], 0, 0, 0);
;             AT_EXP(s0, 8, p1);
;             __builtin_amdgcn_sched_barrier(0);
; #pragma unroll
;             for (int db = 0; db < NDB; ++db) o[db] = __builtin_amdgcn_mfma_f32_32x32x16_bf16(va[NDB + db], p1.b, o[db], 0, 0, 0);
;             AT_EXP(s1, 0, p2);
;             __builtin_amdgcn_sched_barrier(0);
; #pragma unroll
;             for (int db = 0; db < NDB; ++db) o[db] = __builtin_amdgcn_mfma_f32_32x32x16_bf16(vc[db], p2.b, o[db], 0, 0, 0);
;             AT_EXP(s1, 8, p3);
;             __builtin_amdgcn_sched_barrier(0);
; #pragma unroll
;             for (int db = 0; db < NDB; ++db) o[db] = __builtin_amdgcn_mfma_f32_32x32x16_bf16(vc[NDB + db], p3.b, o[db], 0, 0, 0);
;             __builtin_amdgcn_sched_barrier(0);
;     ...
;             l_run += ls0 + ls1;
.LSPp_pv:
	s_cmp_eq_u32 s86, 0
	s_cbranch_scc1 .LSPp_pure
	v_mov_b32_e32 v228, 0
	v_mov_b32_e32 v229, 0
	s_waitcnt lgkmcnt(4)
	v_mfma_f32_32x32x16_bf16 v[50:65], v[146:149], v[238:241], v[50:65]
	v_exp_f32_e32 v98, v98
	v_exp_f32_e32 v99, v99
	v_mfma_f32_32x32x16_bf16 v[34:49], v[150:153], v[238:241], v[34:49]
	v_exp_f32_e32 v100, v100
	v_exp_f32_e32 v101, v101
	v_add_f32_e32 v228, v228, v98
	v_add_f32_e32 v229, v229, v99
	v_mfma_f32_32x32x16_bf16 v[18:33], v[154:157], v[238:241], v[18:33]
	v_exp_f32_e32 v102, v102
	v_exp_f32_e32 v103, v103
	v_add_f32_e32 v228, v228, v100
	v_add_f32_e32 v229, v229, v101
	v_mfma_f32_32x32x16_bf16 v[2:17], v[158:161], v[238:241], v[2:17]
	v_exp_f32_e32 v104, v104
	v_exp_f32_e32 v105, v105
	v_add_f32_e32 v228, v228, v102
	v_add_f32_e32 v229, v229, v103
	v_add3_u32 v236, s99, v183, v187
	ds_read_b128 v[146:149], v236 offset:16384
	ds_read_b128 v[150:153], v236 offset:20480
	ds_read_b128 v[154:157], v236 offset:24576
	ds_read_b128 v[158:161], v236 offset:28672
	s_waitcnt lgkmcnt(4)
	v_mfma_f32_32x32x16_bf16 v[50:65], v[130:133], v[242:245], v[50:65]
	v_exp_f32_e32 v106, v106
	v_exp_f32_e32 v107, v107
	v_add_f32_e32 v228, v228, v104
	v_add_f32_e32 v229, v229, v105
	v_cvt_pk_bf16_f32 v238, v98, v99
	v_mfma_f32_32x32x16_bf16 v[34:49], v[134:137], v[242:245], v[34:49]
	v_exp_f32_e32 v108, v108
	v_exp_f32_e32 v109, v109
	v_add_f32_e32 v228, v228, v106
	v_add_f32_e32 v229, v229, v107
	v_cvt_pk_bf16_f32 v239, v100, v101
	v_mfma_f32_32x32x16_bf16 v[18:33], v[138:141], v[242:245], v[18:33]
	v_exp_f32_e32 v110, v110
	v_exp_f32_e32 v111, v111
	v_add_f32_e32 v228, v228, v108
	v_add_f32_e32 v229, v229, v109
	v_cvt_pk_bf16_f32 v240, v102, v103
	v_mfma_f32_32x32x16_bf16 v[2:17], v[142:145], v[242:245], v[2:17]
	v_exp_f32_e32 v112, v112
	v_exp_f32_e32 v113, v113
	v_add_f32_e32 v228, v228, v110
	v_add_f32_e32 v229, v229, v111
	v_cvt_pk_bf16_f32 v241, v104, v105
	v_add3_u32 v237, s99, v190, v187
	ds_read_b128 v[130:133], v237 offset:16384
	ds_read_b128 v[134:137], v237 offset:20480
	ds_read_b128 v[138:141], v237 offset:24576
	ds_read_b128 v[142:145], v237 offset:28672
	s_waitcnt lgkmcnt(4)
	v_mfma_f32_32x32x16_bf16 v[50:65], v[146:149], v[246:249], v[50:65]
	v_exp_f32_e32 v82, v82
	v_exp_f32_e32 v83, v83
	v_add_f32_e32 v228, v228, v112
	v_add_f32_e32 v229, v229, v113
	v_cvt_pk_bf16_f32 v242, v106, v107
	v_mfma_f32_32x32x16_bf16 v[34:49], v[150:153], v[246:249], v[34:49]
	v_exp_f32_e32 v84, v84
	v_exp_f32_e32 v85, v85
	v_add_f32_e32 v228, v228, v82
	v_add_f32_e32 v229, v229, v83
	v_cvt_pk_bf16_f32 v243, v108, v109
	v_mfma_f32_32x32x16_bf16 v[18:33], v[154:157], v[246:249], v[18:33]
	v_exp_f32_e32 v86, v86
	v_exp_f32_e32 v87, v87
	v_add_f32_e32 v228, v228, v84
	v_add_f32_e32 v229, v229, v85
	v_cvt_pk_bf16_f32 v244, v110, v111
	v_mfma_f32_32x32x16_bf16 v[2:17], v[158:161], v[246:249], v[2:17]
	v_exp_f32_e32 v88, v88
	v_exp_f32_e32 v89, v89
	v_add_f32_e32 v228, v228, v86
	v_add_f32_e32 v229, v229, v87
	v_cvt_pk_bf16_f32 v245, v112, v113
	s_waitcnt lgkmcnt(0)
	v_mfma_f32_32x32x16_bf16 v[50:65], v[130:133], v[250:253], v[50:65]
	v_exp_f32_e32 v90, v90
	v_exp_f32_e32 v91, v91
	v_add_f32_e32 v228, v228, v88
	v_add_f32_e32 v229, v229, v89
	v_cvt_pk_bf16_f32 v246, v82, v83
	v_mfma_f32_32x32x16_bf16 v[34:49], v[134:137], v[250:253], v[34:49]
	v_exp_f32_e32 v92, v92
	v_exp_f32_e32 v93, v93
	v_add_f32_e32 v228, v228, v90
	v_add_f32_e32 v229, v229, v91
	v_cvt_pk_bf16_f32 v247, v84, v85
	v_mfma_f32_32x32x16_bf16 v[18:33], v[138:141], v[250:253], v[18:33]
	v_exp_f32_e32 v94, v94
	v_exp_f32_e32 v95, v95
	v_add_f32_e32 v228, v228, v92
	v_add_f32_e32 v229, v229, v93
	v_cvt_pk_bf16_f32 v248, v86, v87
	v_mfma_f32_32x32x16_bf16 v[2:17], v[142:145], v[250:253], v[2:17]
	v_exp_f32_e32 v96, v96
	v_exp_f32_e32 v97, v97
	v_add_f32_e32 v228, v228, v94
	v_add_f32_e32 v229, v229, v95
	v_cvt_pk_bf16_f32 v249, v88, v89
	v_add_f32_e32 v228, v228, v96
	v_add_f32_e32 v229, v229, v97
	v_cvt_pk_bf16_f32 v250, v90, v91
	v_cvt_pk_bf16_f32 v251, v92, v93
	v_cvt_pk_bf16_f32 v252, v94, v95
	v_cvt_pk_bf16_f32 v253, v96, v97
	v_add_f32_e32 v228, v228, v229
	v_cmp_nge_f32_e32 vcc, 0x53800000, v228
	s_cbranch_vccnz .LSPp_redo
	s_add_i32 s86, s86, 1
	s_add_i32 s85, s85, 0x8000
	s_addk_i32 s84, 0x100
	s_add_i32 s83, s83, 64
	s_sub_i32 s82, s82, 64
	v_add_f32_e32 v0, v0, v228
	v_lshl_add_u64 v[172:173], v[172:173], 0, s[48:49]
	s_cmpk_eq_u32 s84, 0x8000
	v_lshl_add_u64 v[174:175], v[174:175], 0, s[60:61]
	s_cbranch_scc0 .LSPp_top
	s_branch .LSPp_exit
; template <bool WIN> ...
;     ...
;             f32x16 s0, s1;
;             const ALAS unsigned char* sb = lds + (tr & (NSTG - 1)) * STAGE;
;             {
;                 bf16x8 ka[8];
; #pragma unroll
;                 for (int ds = 0; ds < 4; ++ds) { ka[2 * ds] = *(const ALAS bf16x8*)(sb + kx[ds]); ka[2 * ds + 1] = *(const ALAS bf16x8*)(sb + kx[ds] + 4096); }
;                 __builtin_amdgcn_sched_barrier(0);
;                 s0 = __builtin_amdgcn_mfma_f32_32x32x16_bf16(ka[0], qf(0), cvec, 0, 0, 0);
;                 s1 = __builtin_amdgcn_mfma_f32_32x32x16_bf16(ka[1], qf(0), cvec, 0, 0, 0);
; #pragma unroll
;                 for (int ds = 1; ds < 4; ++ds) {
;                     s0 = __builtin_amdgcn_mfma_f32_32x32x16_bf16(ka[2 * ds], qf(ds), s0, 0, 0, 0);
;                     s1 = __builtin_amdgcn_mfma_f32_32x32x16_bf16(ka[2 * ds + 1], qf(ds), s1, 0, 0, 0);
;                 }
;             }
;             bf16x8 va[2 * NDB], vc[2 * NDB];
; #pragma unroll
;             for (int kk = 0; kk < 2; ++kk)
; #pragma unroll
;                 for (int db = 0; db < NDB; ++db) va[kk * NDB + db] = *(const ALAS bf16x8*)(sb + vx[kk] + db * 4096);
;             __builtin_amdgcn_sched_barrier(0);
;             if (near) {
;                 const ALAS float* lb = lut + (k0 + 8 * hi - qabs + LUTC);
; #pragma unroll
;                 for (int r = 0; r < 16; ++r) { s0[r] += lb[16 * (r >> 3) + (r & 7)]; s1[r] += lb[32 + 16 * (r >> 3) + (r & 7)];
;                     if ((r & 7) == 7) __builtin_amdgcn_sched_barrier(0); }
;             }
;     ...
;             union PFU { u32x4 u; bf16x8 b; };
;             PFU p0, p1, p2, p3;
;             AT_EXP(s0, 0, p0);
; #pragma unroll
;             for (int kk = 0; kk < 2; ++kk)
; #pragma unroll
;                 for (int db = 0; db < NDB; ++db) vc[kk * NDB + db] = *(const ALAS bf16x8*)(sb + vx[kk + 2] + db * 4096);
;             __builtin_amdgcn_sched_barrier(0);
; #pragma unroll
;             for (int db = 0; db < NDB; ++db) o[db] = __builtin_amdgcn_mfma_f32_32x32x16_bf16(va[db], p0.b, o[db], 0, 0, 0);
;             AT_EXP(s0, 8, p1);
;             __builtin_amdgcn_sched_barrier(0);
; #pragma unroll
;             for (int db = 0; db < NDB; ++db) o[db] = __builtin_amdgcn_mfma_f32_32x32x16_bf16(va[NDB + db], p1.b, o[db], 0, 0, 0);
;             AT_EXP(s1, 0, p2);
;             __builtin_amdgcn_sched_barrier(0);
; #pragma unroll
.LSPp_pure:
	v_exp_f32_e32 v98, v98
	v_exp_f32_e32 v99, v99
	v_exp_f32_e32 v100, v100
	v_exp_f32_e32 v101, v101
	v_exp_f32_e32 v102, v102
	v_exp_f32_e32 v103, v103
	v_exp_f32_e32 v104, v104
	v_exp_f32_e32 v105, v105
	v_cvt_pk_bf16_f32 v238, v98, v99
	v_cvt_pk_bf16_f32 v239, v100, v101
	v_cvt_pk_bf16_f32 v240, v102, v103
	v_cvt_pk_bf16_f32 v241, v104, v105
	v_mov_b32_e32 v228, v98
	v_mov_b32_e32 v229, v102
	v_add_f32_e32 v228, v228, v99
	v_add_f32_e32 v229, v229, v103
	v_add_f32_e32 v228, v228, v100
	v_add_f32_e32 v229, v229, v104
	v_add_f32_e32 v228, v228, v101
	v_add_f32_e32 v229, v229, v105
	v_exp_f32_e32 v106, v106
	v_exp_f32_e32 v107, v107
	v_exp_f32_e32 v108, v108
	v_exp_f32_e32 v109, v109
	v_exp_f32_e32 v110, v110
	v_exp_f32_e32 v111, v111
	v_exp_f32_e32 v112, v112
	v_exp_f32_e32 v113, v113
	v_cvt_pk_bf16_f32 v242, v106, v107
	v_cvt_pk_bf16_f32 v243, v108, v109
	v_cvt_pk_bf16_f32 v244, v110, v111
	v_cvt_pk_bf16_f32 v245, v112, v113
	v_add_f32_e32 v228, v228, v106
	v_add_f32_e32 v229, v229, v110
	v_add_f32_e32 v228, v228, v107
	v_add_f32_e32 v229, v229, v111
	v_add_f32_e32 v228, v228, v108
	v_add_f32_e32 v229, v229, v112
	v_add_f32_e32 v228, v228, v109
	v_add_f32_e32 v229, v229, v113
	v_exp_f32_e32 v82, v82
	v_exp_f32_e32 v83, v83
	v_exp_f32_e32 v84, v84
	v_exp_f32_e32 v85, v85
	v_exp_f32_e32 v86, v86
	v_exp_f32_e32 v87, v87
	v_exp_f32_e32 v88, v88
	v_exp_f32_e32 v89, v89
	v_cvt_pk_bf16_f32 v246, v82, v83
	v_cvt_pk_bf16_f32 v247, v84, v85
	v_cvt_pk_bf16_f32 v248, v86, v87
	v_cvt_pk_bf16_f32 v249, v88, v89
	v_add_f32_e32 v228, v228, v82
	v_add_f32_e32 v229, v229, v86
	v_add_f32_e32 v228, v228, v83
	v_add_f32_e32 v229, v229, v87
	v_add_f32_e32 v228, v228, v84
	v_add_f32_e32 v229, v229, v88
	v_add_f32_e32 v228, v228, v85
	v_add_f32_e32 v229, v229, v89
	v_exp_f32_e32 v90, v90
	v_exp_f32_e32 v91, v91
	v_exp_f32_e32 v92, v92
	v_exp_f32_e32 v93, v93
	v_exp_f32_e32 v94, v94
	v_exp_f32_e32 v95, v95
	v_exp_f32_e32 v96, v96
	v_exp_f32_e32 v97, v97
	v_cvt_pk_bf16_f32 v250, v90, v91
	v_cvt_pk_bf16_f32 v251, v92, v93
	v_cvt_pk_bf16_f32 v252, v94, v95
	v_cvt_pk_bf16_f32 v253, v96, v97
	v_add_f32_e32 v228, v228, v90
	v_add_f32_e32 v229, v229, v94
	v_add_f32_e32 v228, v228, v91
	v_add_f32_e32 v229, v229, v95
	v_add_f32_e32 v228, v228, v92
	v_add_f32_e32 v229, v229, v96
	v_add_f32_e32 v228, v228, v93
	v_add_f32_e32 v229, v229, v97
	v_add_f32_e32 v228, v228, v229
	v_cmp_nge_f32_e32 vcc, 0x53800000, v228
	s_cbranch_vccnz .LSPp_redo
	s_add_i32 s86, s86, 1
	s_add_i32 s85, s85, 0x8000
	s_addk_i32 s84, 0x100
	s_add_i32 s83, s83, 64
	s_sub_i32 s82, s82, 64
	v_add_f32_e32 v0, v0, v228
	v_lshl_add_u64 v[172:173], v[172:173], 0, s[48:49]
	s_cmpk_eq_u32 s84, 0x8000
	v_lshl_add_u64 v[174:175], v[174:175], 0, s[60:61]
	s_cbranch_scc0 .LSPp_top
	s_branch .LSPp_exit
.LSPp_redo:
	v_add3_u32 v203, s87, v178, v162
	ds_read_b128 v[130:133], v203
	ds_read_b128 v[134:137], v203 offset:4096
	v_add3_u32 v203, s87, v180, v162
	ds_read_b128 v[138:141], v203
	ds_read_b128 v[142:145], v203 offset:4096
	v_add3_u32 v203, s87, v182, v162
	ds_read_b128 v[146:149], v203
	ds_read_b128 v[150:153], v203 offset:4096
	v_add3_u32 v203, s87, v184, v162
	ds_read_b128 v[158:161], v203
	ds_read_b128 v[204:207], v203 offset:4096
	s_waitcnt lgkmcnt(0)
	v_mfma_f32_32x32x16_bf16 v[98:113], v[130:133], v[126:129], v[66:81]
	v_mfma_f32_32x32x16_bf16 v[82:97], v[134:137], v[126:129], v[66:81]
	v_mfma_f32_32x32x16_bf16 v[98:113], v[138:141], v[122:125], v[98:113]
	v_mfma_f32_32x32x16_bf16 v[82:97], v[142:145], v[122:125], v[82:97]
	v_mfma_f32_32x32x16_bf16 v[98:113], v[146:149], v[118:121], v[98:113]
	v_mfma_f32_32x32x16_bf16 v[82:97], v[150:153], v[118:121], v[82:97]
	v_mfma_f32_32x32x16_bf16 v[98:113], v[158:161], v[114:117], v[98:113]
	v_mfma_f32_32x32x16_bf16 v[82:97], v[204:207], v[114:117], v[82:97]
	s_nop 7
	s_nop 7
	s_andn2_b64 vcc, exec, s[64:65]
	s_cbranch_vccnz .LSPp_redomax
	v_add_u32_e32 v203, s84, v171
	v_add_u32_e32 v204, 0x23b80, v203
	v_add_u32_e32 v206, 0x23c00, v203
	v_add_u32_e32 v210, 0x23c08, v203
	v_add_u32_e32 v208, 0x23b88, v203
	v_add_u32_e32 v218, 0x23c10, v203
	v_add_u32_e32 v212, 0x23b90, v203
	v_add_u32_e32 v216, 0x23c18, v203
	v_add_u32_e32 v214, 0x23b98, v203
	ds_read2_b32 v[204:205], v204 offset1:1
	ds_read2_b32 v[206:207], v206 offset1:1
	ds_read2_b32 v[208:209], v208 offset1:1
	ds_read2_b32 v[210:211], v210 offset1:1
	ds_read2_b32 v[212:213], v212 offset1:1
	ds_read2_b32 v[214:215], v214 offset1:1
	ds_read2_b32 v[216:217], v216 offset1:1
	ds_read2_b32 v[218:219], v218 offset1:1
	v_add_u32_e32 v220, 0x23bc0, v203
	v_add_u32_e32 v222, 0x23c40, v203
	v_add_u32_e32 v226, 0x23c48, v203
	v_add_u32_e32 v224, 0x23bc8, v203
	v_add_u32_e32 v228, 0x23bd0, v203
	v_add_u32_e32 v234, 0x23c58, v203
	ds_read2_b32 v[220:221], v220 offset1:1
	ds_read2_b32 v[222:223], v222 offset1:1
	ds_read2_b32 v[224:225], v224 offset1:1
	ds_read2_b32 v[226:227], v226 offset1:1
	v_add_u32_e32 v231, 0x23c50, v203
	v_add_u32_e32 v203, 0x23bd8, v203
	ds_read2_b32 v[228:229], v228 offset1:1
	ds_read2_b32 v[232:233], v203 offset1:1
	ds_read2_b32 v[234:235], v234 offset1:1
	ds_read2_b32 v[236:237], v231 offset1:1
	s_waitcnt lgkmcnt(10)
	v_pk_add_f32 v[104:105], v[104:105], v[214:215]
	v_pk_add_f32 v[102:103], v[102:103], v[212:213]
	v_pk_add_f32 v[100:101], v[100:101], v[208:209]
	s_waitcnt lgkmcnt(2)
	v_pk_add_f32 v[112:113], v[112:113], v[232:233]
	v_pk_add_f32 v[110:111], v[110:111], v[228:229]
	v_pk_add_f32 v[108:109], v[108:109], v[224:225]
	v_pk_add_f32 v[106:107], v[106:107], v[220:221]
	v_pk_add_f32 v[98:99], v[98:99], v[204:205]
	v_pk_add_f32 v[88:89], v[88:89], v[216:217]
	v_pk_add_f32 v[86:87], v[86:87], v[218:219]
	v_pk_add_f32 v[84:85], v[84:85], v[210:211]
	s_waitcnt lgkmcnt(1)
	v_pk_add_f32 v[96:97], v[96:97], v[234:235]
	s_waitcnt lgkmcnt(0)
	v_pk_add_f32 v[94:95], v[94:95], v[236:237]
	v_pk_add_f32 v[92:93], v[92:93], v[226:227]
	v_pk_add_f32 v[90:91], v[90:91], v[222:223]
	v_pk_add_f32 v[82:83], v[82:83], v[206:207]
; #define MX3(a, b, c) __builtin_fmaxf(__builtin_fmaxf((a), (b)), (c))
; template <bool WIN> ...
;     ...
;             float mxa = MX3(s0[0], s0[1], s1[0]), mxb = MX3(s0[2], s0[3], s1[1]);
;             mxa = MX3(mxa, s1[2], s1[3]);
; #pragma unroll
;             for (int r = 4; r < 16; r += 4) { mxa = MX3(mxa, s0[r], s0[r + 1]); mxb = MX3(mxb, s0[r + 2], s0[r + 3]); mxa = MX3(mxa, s1[r], s1[r + 1]); mxb = MX3(mxb, s1[r + 2], s1[r + 3]); }
;     ...
;             float mx = fmaxf(mxa, mxb);
;             if (__any(mx > THR)) {
;                 mx = fmaxf(mx, __shfl_xor(mx, 32));
;                 const float dl = fmaxf(mx, 0.f);
;                 m_ref += dl;
;                 const float f = __builtin_amdgcn_exp2f(-dl);
;                 l_run *= f;
; #pragma unroll
;                 for (int db = 0; db < NDB; ++db)
; #pragma unroll
;                     for (int r = 0; r < 16; ++r) o[db][r] *= f;
; #pragma unroll
;                 for (int r = 0; r < 16; ++r) { s0[r] -= dl; s1[r] -= dl; cvec[r] = cbase - m_ref; }
;             }
.LSPp_redomax:
	s_nop 0
	v_max_f32_e32 v203, v99, v99
	v_max_f32_e32 v204, v98, v98
	v_max_f32_e32 v203, v204, v203
	s_nop 5
	v_max3_f32 v204, v100, v101, v83
	v_max3_f32 v203, v203, v82, v84
	v_max3_f32 v203, v203, v85, v102
	v_max3_f32 v204, v204, v104, v105
	v_max3_f32 v203, v203, v103, v86
	v_max3_f32 v204, v204, v88, v89
	v_max3_f32 v203, v203, v87, v106
	v_max3_f32 v204, v204, v108, v109
	v_max3_f32 v203, v203, v107, v90
	v_max3_f32 v204, v204, v92, v93
	v_max3_f32 v203, v203, v91, v110
	v_max3_f32 v204, v204, v112, v113
	v_max3_f32 v203, v203, v111, v94
	v_max3_f32 v204, v204, v96, v97
	v_max3_f32 v203, v203, v95, v204
	ds_bpermute_b32 v66, v176, v203
	s_waitcnt lgkmcnt(0)
	v_max3_f32 v68, v203, v66, 0
	v_exp_f32_e64 v70, -v68
	v_add_f32_e32 v196, v196, v68
	v_sub_f32_e32 v66, v202, v196
	v_pk_add_f32 v[98:99], v[98:99], v[68:69] op_sel_hi:[1,0] neg_lo:[0,1] neg_hi:[0,1]
	v_pk_mul_f32 v[64:65], v[64:65], v[70:71] op_sel_hi:[1,0]
	v_pk_mul_f32 v[62:63], v[62:63], v[70:71] op_sel_hi:[1,0]
	v_pk_mul_f32 v[60:61], v[60:61], v[70:71] op_sel_hi:[1,0]
	v_pk_mul_f32 v[58:59], v[58:59], v[70:71] op_sel_hi:[1,0]
	v_pk_mul_f32 v[56:57], v[56:57], v[70:71] op_sel_hi:[1,0]
	v_pk_mul_f32 v[54:55], v[54:55], v[70:71] op_sel_hi:[1,0]
	v_pk_mul_f32 v[52:53], v[52:53], v[70:71] op_sel_hi:[1,0]
	v_pk_mul_f32 v[50:51], v[50:51], v[70:71] op_sel_hi:[1,0]
	v_pk_mul_f32 v[48:49], v[48:49], v[70:71] op_sel_hi:[1,0]
	v_pk_mul_f32 v[46:47], v[46:47], v[70:71] op_sel_hi:[1,0]
	v_pk_mul_f32 v[44:45], v[44:45], v[70:71] op_sel_hi:[1,0]
	v_pk_mul_f32 v[42:43], v[42:43], v[70:71] op_sel_hi:[1,0]
	v_pk_mul_f32 v[40:41], v[40:41], v[70:71] op_sel_hi:[1,0]
	v_pk_mul_f32 v[38:39], v[38:39], v[70:71] op_sel_hi:[1,0]
	v_pk_mul_f32 v[36:37], v[36:37], v[70:71] op_sel_hi:[1,0]
	v_pk_mul_f32 v[34:35], v[34:35], v[70:71] op_sel_hi:[1,0]
	v_pk_mul_f32 v[32:33], v[32:33], v[70:71] op_sel_hi:[1,0]
	v_pk_mul_f32 v[30:31], v[30:31], v[70:71] op_sel_hi:[1,0]
	v_pk_mul_f32 v[28:29], v[28:29], v[70:71] op_sel_hi:[1,0]
	v_pk_mul_f32 v[26:27], v[26:27], v[70:71] op_sel_hi:[1,0]
	v_pk_mul_f32 v[24:25], v[24:25], v[70:71] op_sel_hi:[1,0]
	v_pk_mul_f32 v[22:23], v[22:23], v[70:71] op_sel_hi:[1,0]
	v_pk_mul_f32 v[20:21], v[20:21], v[70:71] op_sel_hi:[1,0]
	v_pk_mul_f32 v[18:19], v[18:19], v[70:71] op_sel_hi:[1,0]
	v_pk_mul_f32 v[16:17], v[16:17], v[70:71] op_sel_hi:[1,0]
	v_pk_mul_f32 v[14:15], v[14:15], v[70:71] op_sel_hi:[1,0]
	v_pk_mul_f32 v[12:13], v[12:13], v[70:71] op_sel_hi:[1,0]
	v_pk_mul_f32 v[10:11], v[10:11], v[70:71] op_sel_hi:[1,0]
	v_pk_mul_f32 v[8:9], v[8:9], v[70:71] op_sel_hi:[1,0]
	v_pk_mul_f32 v[6:7], v[6:7], v[70:71] op_sel_hi:[1,0]
	v_pk_mul_f32 v[4:5], v[4:5], v[70:71] op_sel_hi:[1,0]
	v_pk_mul_f32 v[2:3], v[2:3], v[70:71] op_sel_hi:[1,0]
	v_pk_add_f32 v[82:83], v[82:83], v[68:69] op_sel_hi:[1,0] neg_lo:[0,1] neg_hi:[0,1]
	v_pk_add_f32 v[100:101], v[100:101], v[68:69] op_sel_hi:[1,0] neg_lo:[0,1] neg_hi:[0,1]
	v_pk_add_f32 v[84:85], v[84:85], v[68:69] op_sel_hi:[1,0] neg_lo:[0,1] neg_hi:[0,1]
	v_pk_add_f32 v[102:103], v[102:103], v[68:69] op_sel_hi:[1,0] neg_lo:[0,1] neg_hi:[0,1]
	v_pk_add_f32 v[86:87], v[86:87], v[68:69] op_sel_hi:[1,0] neg_lo:[0,1] neg_hi:[0,1]
	v_pk_add_f32 v[104:105], v[104:105], v[68:69] op_sel_hi:[1,0] neg_lo:[0,1] neg_hi:[0,1]
	v_pk_add_f32 v[88:89], v[88:89], v[68:69] op_sel_hi:[1,0] neg_lo:[0,1] neg_hi:[0,1]
	v_pk_add_f32 v[106:107], v[106:107], v[68:69] op_sel_hi:[1,0] neg_lo:[0,1] neg_hi:[0,1]
	v_pk_add_f32 v[90:91], v[90:91], v[68:69] op_sel_hi:[1,0] neg_lo:[0,1] neg_hi:[0,1]
	v_pk_add_f32 v[108:109], v[108:109], v[68:69] op_sel_hi:[1,0] neg_lo:[0,1] neg_hi:[0,1]
	v_pk_add_f32 v[92:93], v[92:93], v[68:69] op_sel_hi:[1,0] neg_lo:[0,1] neg_hi:[0,1]
	v_pk_add_f32 v[110:111], v[110:111], v[68:69] op_sel_hi:[1,0] neg_lo:[0,1] neg_hi:[0,1]
	v_pk_add_f32 v[94:95], v[94:95], v[68:69] op_sel_hi:[1,0] neg_lo:[0,1] neg_hi:[0,1]
	v_pk_add_f32 v[112:113], v[112:113], v[68:69] op_sel_hi:[1,0] neg_lo:[0,1] neg_hi:[0,1]
	v_pk_add_f32 v[96:97], v[96:97], v[68:69] op_sel_hi:[1,0] neg_lo:[0,1] neg_hi:[0,1]
	v_mul_f32_e32 v0, v0, v70
	v_mov_b32_e32 v67, v66
	v_mov_b32_e32 v68, v66
	v_mov_b32_e32 v69, v66
	v_mov_b32_e32 v70, v66
	v_mov_b32_e32 v71, v66
	v_mov_b32_e32 v72, v66
	v_mov_b32_e32 v73, v66
	v_mov_b32_e32 v74, v66
	v_mov_b32_e32 v75, v66
	v_mov_b32_e32 v76, v66
	v_mov_b32_e32 v77, v66
	v_mov_b32_e32 v78, v66
	v_mov_b32_e32 v79, v66
	v_mov_b32_e32 v80, v66
	v_mov_b32_e32 v81, v66
	s_branch .LSPp_pure2

; #define ALAS __attribute__((address_space(3)))
; template <bool WIN> ...
;     ...
;             float ls0 = 0.f, ls1 = 0.f;
;     ...
;             union PFU { u32x4 u; bf16x8 b; };
;             PFU p0, p1, p2, p3;
;             AT_EXP(s0, 0, p0);
; #pragma unroll
;             for (int kk = 0; kk < 2; ++kk)
; #pragma unroll
;                 for (int db = 0; db < NDB; ++db) vc[kk * NDB + db] = *(const ALAS bf16x8*)(sb + vx[kk + 2] + db * 4096);
;             __builtin_amdgcn_sched_barrier(0);
; #pragma unroll
;             for (int db = 0; db < NDB; ++db) o[db] = __builtin_amdgcn_mfma_f32_32x32x16_bf16(va[db], p0.b, o[db], 0, 0, 0);
;             AT_EXP(s0, 8, p1);
;             __builtin_amdgcn_sched_barrier(0);
; #pragma unroll
;             for (int db = 0; db < NDB; ++db) o[db] = __builtin_amdgcn_mfma_f32_32x32x16_bf16(va[NDB + db], p1.b, o[db], 0, 0, 0);
;             AT_EXP(s1, 0, p2);
;             __builtin_amdgcn_sched_barrier(0);
; #pragma unroll
;             for (int db = 0; db < NDB; ++db) o[db] = __builtin_amdgcn_mfma_f32_32x32x16_bf16(vc[db], p2.b, o[db], 0, 0, 0);
;             AT_EXP(s1, 8, p3);
;             __builtin_amdgcn_sched_barrier(0);
; #pragma unroll
;             for (int db = 0; db < NDB; ++db) o[db] = __builtin_amdgcn_mfma_f32_32x32x16_bf16(vc[NDB + db], p3.b, o[db], 0, 0, 0);
;             __builtin_amdgcn_sched_barrier(0);
;     ...
;             l_run += ls0 + ls1;
.LSPs_pv:
	s_cmp_eq_u32 s79, 0
	s_cbranch_scc1 .LSPs_pure
	v_mov_b32_e32 v228, 0
	v_mov_b32_e32 v229, 0
	s_waitcnt lgkmcnt(4)
	v_mfma_f32_32x32x16_bf16 v[50:65], v[146:149], v[238:241], v[50:65]
	v_exp_f32_e32 v98, v98
	v_exp_f32_e32 v99, v99
	v_mfma_f32_32x32x16_bf16 v[34:49], v[150:153], v[238:241], v[34:49]
	v_exp_f32_e32 v100, v100
	v_exp_f32_e32 v101, v101
	v_add_f32_e32 v228, v228, v98
	v_add_f32_e32 v229, v229, v99
	v_mfma_f32_32x32x16_bf16 v[18:33], v[154:157], v[238:241], v[18:33]
	v_exp_f32_e32 v102, v102
	v_exp_f32_e32 v103, v103
	v_add_f32_e32 v228, v228, v100
	v_add_f32_e32 v229, v229, v101
	v_mfma_f32_32x32x16_bf16 v[2:17], v[158:161], v[238:241], v[2:17]
	v_exp_f32_e32 v104, v104
	v_exp_f32_e32 v105, v105
	v_add_f32_e32 v228, v228, v102
	v_add_f32_e32 v229, v229, v103
	v_add3_u32 v236, s99, v183, v187
	ds_read_b128 v[146:149], v236 offset:16384
	ds_read_b128 v[150:153], v236 offset:20480
	ds_read_b128 v[154:157], v236 offset:24576
	ds_read_b128 v[158:161], v236 offset:28672
	s_waitcnt lgkmcnt(4)
	v_mfma_f32_32x32x16_bf16 v[50:65], v[130:133], v[242:245], v[50:65]
	v_exp_f32_e32 v106, v106
	v_exp_f32_e32 v107, v107
	v_add_f32_e32 v228, v228, v104
	v_add_f32_e32 v229, v229, v105
	v_cvt_pk_bf16_f32 v238, v98, v99
	v_mfma_f32_32x32x16_bf16 v[34:49], v[134:137], v[242:245], v[34:49]
	v_exp_f32_e32 v108, v108
	v_exp_f32_e32 v109, v109
	v_add_f32_e32 v228, v228, v106
	v_add_f32_e32 v229, v229, v107
	v_cvt_pk_bf16_f32 v239, v100, v101
	v_mfma_f32_32x32x16_bf16 v[18:33], v[138:141], v[242:245], v[18:33]
	v_exp_f32_e32 v110, v110
	v_exp_f32_e32 v111, v111
	v_add_f32_e32 v228, v228, v108
	v_add_f32_e32 v229, v229, v109
	v_cvt_pk_bf16_f32 v240, v102, v103
	v_mfma_f32_32x32x16_bf16 v[2:17], v[142:145], v[242:245], v[2:17]
	v_exp_f32_e32 v112, v112
	v_exp_f32_e32 v113, v113
	v_add_f32_e32 v228, v228, v110
	v_add_f32_e32 v229, v229, v111
	v_cvt_pk_bf16_f32 v241, v104, v105
	v_add3_u32 v237, s99, v190, v187
	ds_read_b128 v[130:133], v237 offset:16384
	ds_read_b128 v[134:137], v237 offset:20480
	ds_read_b128 v[138:141], v237 offset:24576
	ds_read_b128 v[142:145], v237 offset:28672
	s_waitcnt lgkmcnt(4)
	v_mfma_f32_32x32x16_bf16 v[50:65], v[146:149], v[246:249], v[50:65]
	v_exp_f32_e32 v82, v82
	v_exp_f32_e32 v83, v83
	v_add_f32_e32 v228, v228, v112
	v_add_f32_e32 v229, v229, v113
	v_cvt_pk_bf16_f32 v242, v106, v107
	v_mfma_f32_32x32x16_bf16 v[34:49], v[150:153], v[246:249], v[34:49]
	v_exp_f32_e32 v84, v84
	v_exp_f32_e32 v85, v85
	v_add_f32_e32 v228, v228, v82
	v_add_f32_e32 v229, v229, v83
	v_cvt_pk_bf16_f32 v243, v108, v109
	v_mfma_f32_32x32x16_bf16 v[18:33], v[154:157], v[246:249], v[18:33]
	v_exp_f32_e32 v86, v86
	v_exp_f32_e32 v87, v87
	v_add_f32_e32 v228, v228, v84
	v_add_f32_e32 v229, v229, v85
	v_cvt_pk_bf16_f32 v244, v110, v111
	v_mfma_f32_32x32x16_bf16 v[2:17], v[158:161], v[246:249], v[2:17]
	v_exp_f32_e32 v88, v88
	v_exp_f32_e32 v89, v89
	v_add_f32_e32 v228, v228, v86
	v_add_f32_e32 v229, v229, v87
	v_cvt_pk_bf16_f32 v245, v112, v113
	s_waitcnt lgkmcnt(0)
	v_mfma_f32_32x32x16_bf16 v[50:65], v[130:133], v[250:253], v[50:65]
	v_exp_f32_e32 v90, v90
	v_exp_f32_e32 v91, v91
	v_add_f32_e32 v228, v228, v88
	v_add_f32_e32 v229, v229, v89
	v_cvt_pk_bf16_f32 v246, v82, v83
	v_mfma_f32_32x32x16_bf16 v[34:49], v[134:137], v[250:253], v[34:49]
	v_exp_f32_e32 v92, v92
	v_exp_f32_e32 v93, v93
	v_add_f32_e32 v228, v228, v90
	v_add_f32_e32 v229, v229, v91
	v_cvt_pk_bf16_f32 v247, v84, v85
	v_mfma_f32_32x32x16_bf16 v[18:33], v[138:141], v[250:253], v[18:33]
	v_exp_f32_e32 v94, v94
	v_exp_f32_e32 v95, v95
	v_add_f32_e32 v228, v228, v92
	v_add_f32_e32 v229, v229, v93
	v_cvt_pk_bf16_f32 v248, v86, v87
	v_mfma_f32_32x32x16_bf16 v[2:17], v[142:145], v[250:253], v[2:17]
	v_exp_f32_e32 v96, v96
	v_exp_f32_e32 v97, v97
	v_add_f32_e32 v228, v228, v94
	v_add_f32_e32 v229, v229, v95
	v_cvt_pk_bf16_f32 v249, v88, v89
	v_add_f32_e32 v228, v228, v96
	v_add_f32_e32 v229, v229, v97
	v_cvt_pk_bf16_f32 v250, v90, v91
	v_cvt_pk_bf16_f32 v251, v92, v93
	v_cvt_pk_bf16_f32 v252, v94, v95
	v_cvt_pk_bf16_f32 v253, v96, v97
	v_add_f32_e32 v228, v228, v229
	v_cmp_nge_f32_e32 vcc, 0x53800000, v228
	s_cbranch_vccnz .LSPs_redo
	s_add_i32 s79, s79, 1
	s_add_i32 s78, s78, 0x8000
	s_addk_i32 s77, 0x100
	s_add_i32 s76, s76, 64
	v_add_f32_e32 v0, v0, v228
	v_lshl_add_u64 v[172:173], v[172:173], 0, s[48:49]
	s_cmpk_eq_i32 s77, 0x2000
	v_lshl_add_u64 v[174:175], v[174:175], 0, s[60:61]
	s_cbranch_scc0 .LSPs_top
	s_branch .LSPs_exit
; template <bool WIN> ...
;     ...
;             f32x16 s0, s1;
;             const ALAS unsigned char* sb = lds + (tr & (NSTG - 1)) * STAGE;
;             {
;                 bf16x8 ka[8];
; #pragma unroll
;                 for (int ds = 0; ds < 4; ++ds) { ka[2 * ds] = *(const ALAS bf16x8*)(sb + kx[ds]); ka[2 * ds + 1] = *(const ALAS bf16x8*)(sb + kx[ds] + 4096); }
;                 __builtin_amdgcn_sched_barrier(0);
;                 s0 = __builtin_amdgcn_mfma_f32_32x32x16_bf16(ka[0], qf(0), cvec, 0, 0, 0);
;                 s1 = __builtin_amdgcn_mfma_f32_32x32x16_bf16(ka[1], qf(0), cvec, 0, 0, 0);
; #pragma unroll
;                 for (int ds = 1; ds < 4; ++ds) {
;                     s0 = __builtin_amdgcn_mfma_f32_32x32x16_bf16(ka[2 * ds], qf(ds), s0, 0, 0, 0);
;                     s1 = __builtin_amdgcn_mfma_f32_32x32x16_bf16(ka[2 * ds + 1], qf(ds), s1, 0, 0, 0);
;                 }
;             }
;             bf16x8 va[2 * NDB], vc[2 * NDB];
; #pragma unroll
;             for (int kk = 0; kk < 2; ++kk)
; #pragma unroll
;                 for (int db = 0; db < NDB; ++db) va[kk * NDB + db] = *(const ALAS bf16x8*)(sb + vx[kk] + db * 4096);
;             __builtin_amdgcn_sched_barrier(0);
;             if (near) {
;                 const ALAS float* lb = lut + (k0 + 8 * hi - qabs + LUTC);
; #pragma unroll
;                 for (int r = 0; r < 16; ++r) { s0[r] += lb[16 * (r >> 3) + (r & 7)]; s1[r] += lb[32 + 16 * (r >> 3) + (r & 7)];
;                     if ((r & 7) == 7) __builtin_amdgcn_sched_barrier(0); }
;             }
;     ...
;             union PFU { u32x4 u; bf16x8 b; };
;             PFU p0, p1, p2, p3;
;             AT_EXP(s0, 0, p0);
; #pragma unroll
;             for (int kk = 0; kk < 2; ++kk)
; #pragma unroll
;                 for (int db = 0; db < NDB; ++db) vc[kk * NDB + db] = *(const ALAS bf16x8*)(sb + vx[kk + 2] + db * 4096);
;             __builtin_amdgcn_sched_barrier(0);
; #pragma unroll
;             for (int db = 0; db < NDB; ++db) o[db] = __builtin_amdgcn_mfma_f32_32x32x16_bf16(va[db], p0.b, o[db], 0, 0, 0);
;             AT_EXP(s0, 8, p1);
;             __builtin_amdgcn_sched_barrier(0);
; #pragma unroll
;             for (int db = 0; db < NDB; ++db) o[db] = __builtin_amdgcn_mfma_f32_32x32x16_bf16(va[NDB + db], p1.b, o[db], 0, 0, 0);
;             AT_EXP(s1, 0, p2);
;             __builtin_amdgcn_sched_barrier(0);
; #pragma unroll
.LSPs_pure:
	v_exp_f32_e32 v98, v98
	v_exp_f32_e32 v99, v99
	v_exp_f32_e32 v100, v100
	v_exp_f32_e32 v101, v101
	v_exp_f32_e32 v102, v102
	v_exp_f32_e32 v103, v103
	v_exp_f32_e32 v104, v104
	v_exp_f32_e32 v105, v105
	v_cvt_pk_bf16_f32 v238, v98, v99
	v_cvt_pk_bf16_f32 v239, v100, v101
	v_cvt_pk_bf16_f32 v240, v102, v103
	v_cvt_pk_bf16_f32 v241, v104, v105
	v_mov_b32_e32 v228, v98
	v_mov_b32_e32 v229, v102
	v_add_f32_e32 v228, v228, v99
	v_add_f32_e32 v229, v229, v103
	v_add_f32_e32 v228, v228, v100
	v_add_f32_e32 v229, v229, v104
	v_add_f32_e32 v228, v228, v101
	v_add_f32_e32 v229, v229, v105
	v_exp_f32_e32 v106, v106
	v_exp_f32_e32 v107, v107
	v_exp_f32_e32 v108, v108
	v_exp_f32_e32 v109, v109
	v_exp_f32_e32 v110, v110
	v_exp_f32_e32 v111, v111
	v_exp_f32_e32 v112, v112
	v_exp_f32_e32 v113, v113
	v_cvt_pk_bf16_f32 v242, v106, v107
	v_cvt_pk_bf16_f32 v243, v108, v109
	v_cvt_pk_bf16_f32 v244, v110, v111
	v_cvt_pk_bf16_f32 v245, v112, v113
	v_add_f32_e32 v228, v228, v106
	v_add_f32_e32 v229, v229, v110
	v_add_f32_e32 v228, v228, v107
	v_add_f32_e32 v229, v229, v111
	v_add_f32_e32 v228, v228, v108
	v_add_f32_e32 v229, v229, v112
	v_add_f32_e32 v228, v228, v109
	v_add_f32_e32 v229, v229, v113
	v_exp_f32_e32 v82, v82
	v_exp_f32_e32 v83, v83
	v_exp_f32_e32 v84, v84
	v_exp_f32_e32 v85, v85
	v_exp_f32_e32 v86, v86
	v_exp_f32_e32 v87, v87
	v_exp_f32_e32 v88, v88
	v_exp_f32_e32 v89, v89
	v_cvt_pk_bf16_f32 v246, v82, v83
	v_cvt_pk_bf16_f32 v247, v84, v85
	v_cvt_pk_bf16_f32 v248, v86, v87
	v_cvt_pk_bf16_f32 v249, v88, v89
	v_add_f32_e32 v228, v228, v82
	v_add_f32_e32 v229, v229, v86
	v_add_f32_e32 v228, v228, v83
	v_add_f32_e32 v229, v229, v87
	v_add_f32_e32 v228, v228, v84
	v_add_f32_e32 v229, v229, v88
	v_add_f32_e32 v228, v228, v85
	v_add_f32_e32 v229, v229, v89
	v_exp_f32_e32 v90, v90
	v_exp_f32_e32 v91, v91
	v_exp_f32_e32 v92, v92
	v_exp_f32_e32 v93, v93
	v_exp_f32_e32 v94, v94
	v_exp_f32_e32 v95, v95
	v_exp_f32_e32 v96, v96
	v_exp_f32_e32 v97, v97
	v_cvt_pk_bf16_f32 v250, v90, v91
	v_cvt_pk_bf16_f32 v251, v92, v93
	v_cvt_pk_bf16_f32 v252, v94, v95
	v_cvt_pk_bf16_f32 v253, v96, v97
	v_add_f32_e32 v228, v228, v90
	v_add_f32_e32 v229, v229, v94
	v_add_f32_e32 v228, v228, v91
	v_add_f32_e32 v229, v229, v95
	v_add_f32_e32 v228, v228, v92
	v_add_f32_e32 v229, v229, v96
	v_add_f32_e32 v228, v228, v93
	v_add_f32_e32 v229, v229, v97
	v_add_f32_e32 v228, v228, v229
	v_cmp_nge_f32_e32 vcc, 0x53800000, v228
	s_cbranch_vccnz .LSPs_redo
	s_add_i32 s79, s79, 1
	s_add_i32 s78, s78, 0x8000
	s_addk_i32 s77, 0x100
	s_add_i32 s76, s76, 64
	v_add_f32_e32 v0, v0, v228
	v_lshl_add_u64 v[172:173], v[172:173], 0, s[48:49]
	s_cmpk_eq_i32 s77, 0x2000
	v_lshl_add_u64 v[174:175], v[174:175], 0, s[60:61]
	s_cbranch_scc0 .LSPs_top
	s_branch .LSPs_exit
.LSPs_redo:
	v_add3_u32 v203, s80, v178, v162
	ds_read_b128 v[130:133], v203
	ds_read_b128 v[134:137], v203 offset:4096
	v_add3_u32 v203, s80, v180, v162
	ds_read_b128 v[138:141], v203
	ds_read_b128 v[142:145], v203 offset:4096
	v_add3_u32 v203, s80, v182, v162
	ds_read_b128 v[146:149], v203
	ds_read_b128 v[150:153], v203 offset:4096
	v_add3_u32 v203, s80, v184, v162
	ds_read_b128 v[158:161], v203
	ds_read_b128 v[204:207], v203 offset:4096
	s_waitcnt lgkmcnt(0)
	v_mfma_f32_32x32x16_bf16 v[98:113], v[130:133], v[126:129], v[66:81]
	v_mfma_f32_32x32x16_bf16 v[82:97], v[134:137], v[126:129], v[66:81]
	v_mfma_f32_32x32x16_bf16 v[98:113], v[138:141], v[122:125], v[98:113]
	v_mfma_f32_32x32x16_bf16 v[82:97], v[142:145], v[122:125], v[82:97]
	v_mfma_f32_32x32x16_bf16 v[98:113], v[146:149], v[118:121], v[98:113]
	v_mfma_f32_32x32x16_bf16 v[82:97], v[150:153], v[118:121], v[82:97]
	v_mfma_f32_32x32x16_bf16 v[98:113], v[158:161], v[114:117], v[98:113]
	v_mfma_f32_32x32x16_bf16 v[82:97], v[204:207], v[114:117], v[82:97]
	s_nop 7
	s_nop 7
	s_andn2_b64 vcc, exec, s[64:65]
	s_cbranch_vccnz .LSPs_redomax
	v_add_u32_e32 v203, s77, v171
	v_add_u32_e32 v204, 0x23b80, v203
	v_add_u32_e32 v206, 0x23c00, v203
	v_add_u32_e32 v210, 0x23c08, v203
	v_add_u32_e32 v208, 0x23b88, v203
	v_add_u32_e32 v218, 0x23c10, v203
	v_add_u32_e32 v212, 0x23b90, v203
	v_add_u32_e32 v216, 0x23c18, v203
	v_add_u32_e32 v214, 0x23b98, v203
	ds_read2_b32 v[204:205], v204 offset1:1
	ds_read2_b32 v[206:207], v206 offset1:1
	ds_read2_b32 v[208:209], v208 offset1:1
	ds_read2_b32 v[210:211], v210 offset1:1
	ds_read2_b32 v[212:213], v212 offset1:1
	ds_read2_b32 v[214:215], v214 offset1:1
	ds_read2_b32 v[216:217], v216 offset1:1
	ds_read2_b32 v[218:219], v218 offset1:1
	v_add_u32_e32 v220, 0x23bc0, v203
	v_add_u32_e32 v222, 0x23c40, v203
	v_add_u32_e32 v226, 0x23c48, v203
	v_add_u32_e32 v224, 0x23bc8, v203
	v_add_u32_e32 v228, 0x23bd0, v203
	v_add_u32_e32 v234, 0x23c58, v203
	ds_read2_b32 v[220:221], v220 offset1:1
	ds_read2_b32 v[222:223], v222 offset1:1
	ds_read2_b32 v[224:225], v224 offset1:1
	ds_read2_b32 v[226:227], v226 offset1:1
	v_add_u32_e32 v231, 0x23c50, v203
	v_add_u32_e32 v203, 0x23bd8, v203
	ds_read2_b32 v[228:229], v228 offset1:1
	ds_read2_b32 v[232:233], v203 offset1:1
	ds_read2_b32 v[234:235], v234 offset1:1
	ds_read2_b32 v[236:237], v231 offset1:1
	s_waitcnt lgkmcnt(10)
	v_pk_add_f32 v[104:105], v[104:105], v[214:215]
	v_pk_add_f32 v[102:103], v[102:103], v[212:213]
	v_pk_add_f32 v[100:101], v[100:101], v[208:209]
	s_waitcnt lgkmcnt(2)
	v_pk_add_f32 v[112:113], v[112:113], v[232:233]
	v_pk_add_f32 v[110:111], v[110:111], v[228:229]
	v_pk_add_f32 v[108:109], v[108:109], v[224:225]
	v_pk_add_f32 v[106:107], v[106:107], v[220:221]
	v_pk_add_f32 v[98:99], v[98:99], v[204:205]
	v_pk_add_f32 v[88:89], v[88:89], v[216:217]
	v_pk_add_f32 v[86:87], v[86:87], v[218:219]
	v_pk_add_f32 v[84:85], v[84:85], v[210:211]
	s_waitcnt lgkmcnt(1)
	v_pk_add_f32 v[96:97], v[96:97], v[234:235]
	s_waitcnt lgkmcnt(0)
	v_pk_add_f32 v[94:95], v[94:95], v[236:237]
	v_pk_add_f32 v[92:93], v[92:93], v[226:227]
	v_pk_add_f32 v[90:91], v[90:91], v[222:223]
	v_pk_add_f32 v[82:83], v[82:83], v[206:207]
; #define MX3(a, b, c) __builtin_fmaxf(__builtin_fmaxf((a), (b)), (c))
; template <bool WIN> ...
;     ...
;             float mxa = MX3(s0[0], s0[1], s1[0]), mxb = MX3(s0[2], s0[3], s1[1]);
;             mxa = MX3(mxa, s1[2], s1[3]);
; #pragma unroll
;             for (int r = 4; r < 16; r += 4) { mxa = MX3(mxa, s0[r], s0[r + 1]); mxb = MX3(mxb, s0[r + 2], s0[r + 3]); mxa = MX3(mxa, s1[r], s1[r + 1]); mxb = MX3(mxb, s1[r + 2], s1[r + 3]); }
;     ...
;             float mx = fmaxf(mxa, mxb);
;             if (__any(mx > THR)) {
;                 mx = fmaxf(mx, __shfl_xor(mx, 32));
;                 const float dl = fmaxf(mx, 0.f);
;                 m_ref += dl;
;                 const float f = __builtin_amdgcn_exp2f(-dl);
;                 l_run *= f;
; #pragma unroll
;                 for (int db = 0; db < NDB; ++db)
; #pragma unroll
;                     for (int r = 0; r < 16; ++r) o[db][r] *= f;
; #pragma unroll
;                 for (int r = 0; r < 16; ++r) { s0[r] -= dl; s1[r] -= dl; cvec[r] = cbase - m_ref; }
;             }
.LSPs_redomax:
	s_nop 0
	v_max_f32_e32 v203, v99, v99
	v_max_f32_e32 v204, v98, v98
	v_max_f32_e32 v203, v204, v203
	s_nop 5
	v_max3_f32 v204, v100, v101, v83
	v_max3_f32 v203, v203, v82, v84
	v_max3_f32 v203, v203, v85, v102
	v_max3_f32 v204, v204, v104, v105
	v_max3_f32 v203, v203, v103, v86
	v_max3_f32 v204, v204, v88, v89
	v_max3_f32 v203, v203, v87, v106
	v_max3_f32 v204, v204, v108, v109
	v_max3_f32 v203, v203, v107, v90
	v_max3_f32 v204, v204, v92, v93
	v_max3_f32 v203, v203, v91, v110
	v_max3_f32 v204, v204, v112, v113
	v_max3_f32 v203, v203, v111, v94
	v_max3_f32 v204, v204, v96, v97
	v_max3_f32 v203, v203, v95, v204
	ds_bpermute_b32 v66, v176, v203
	s_waitcnt lgkmcnt(0)
	v_max3_f32 v68, v203, v66, 0
	v_exp_f32_e64 v70, -v68
	v_add_f32_e32 v201, v201, v68
	v_sub_f32_e32 v66, v202, v201
	v_pk_add_f32 v[98:99], v[98:99], v[68:69] op_sel_hi:[1,0] neg_lo:[0,1] neg_hi:[0,1]
	v_pk_mul_f32 v[64:65], v[64:65], v[70:71] op_sel_hi:[1,0]
	v_pk_mul_f32 v[62:63], v[62:63], v[70:71] op_sel_hi:[1,0]
	v_pk_mul_f32 v[60:61], v[60:61], v[70:71] op_sel_hi:[1,0]
	v_pk_mul_f32 v[58:59], v[58:59], v[70:71] op_sel_hi:[1,0]
	v_pk_mul_f32 v[56:57], v[56:57], v[70:71] op_sel_hi:[1,0]
	v_pk_mul_f32 v[54:55], v[54:55], v[70:71] op_sel_hi:[1,0]
	v_pk_mul_f32 v[52:53], v[52:53], v[70:71] op_sel_hi:[1,0]
	v_pk_mul_f32 v[50:51], v[50:51], v[70:71] op_sel_hi:[1,0]
	v_pk_mul_f32 v[48:49], v[48:49], v[70:71] op_sel_hi:[1,0]
	v_pk_mul_f32 v[46:47], v[46:47], v[70:71] op_sel_hi:[1,0]
	v_pk_mul_f32 v[44:45], v[44:45], v[70:71] op_sel_hi:[1,0]
	v_pk_mul_f32 v[42:43], v[42:43], v[70:71] op_sel_hi:[1,0]
	v_pk_mul_f32 v[40:41], v[40:41], v[70:71] op_sel_hi:[1,0]
	v_pk_mul_f32 v[38:39], v[38:39], v[70:71] op_sel_hi:[1,0]
	v_pk_mul_f32 v[36:37], v[36:37], v[70:71] op_sel_hi:[1,0]
	v_pk_mul_f32 v[34:35], v[34:35], v[70:71] op_sel_hi:[1,0]
	v_pk_mul_f32 v[32:33], v[32:33], v[70:71] op_sel_hi:[1,0]
	v_pk_mul_f32 v[30:31], v[30:31], v[70:71] op_sel_hi:[1,0]
	v_pk_mul_f32 v[28:29], v[28:29], v[70:71] op_sel_hi:[1,0]
	v_pk_mul_f32 v[26:27], v[26:27], v[70:71] op_sel_hi:[1,0]
	v_pk_mul_f32 v[24:25], v[24:25], v[70:71] op_sel_hi:[1,0]
	v_pk_mul_f32 v[22:23], v[22:23], v[70:71] op_sel_hi:[1,0]
	v_pk_mul_f32 v[20:21], v[20:21], v[70:71] op_sel_hi:[1,0]
	v_pk_mul_f32 v[18:19], v[18:19], v[70:71] op_sel_hi:[1,0]
	v_pk_mul_f32 v[16:17], v[16:17], v[70:71] op_sel_hi:[1,0]
	v_pk_mul_f32 v[14:15], v[14:15], v[70:71] op_sel_hi:[1,0]
	v_pk_mul_f32 v[12:13], v[12:13], v[70:71] op_sel_hi:[1,0]
	v_pk_mul_f32 v[10:11], v[10:11], v[70:71] op_sel_hi:[1,0]
	v_pk_mul_f32 v[8:9], v[8:9], v[70:71] op_sel_hi:[1,0]
	v_pk_mul_f32 v[6:7], v[6:7], v[70:71] op_sel_hi:[1,0]
	v_pk_mul_f32 v[4:5], v[4:5], v[70:71] op_sel_hi:[1,0]
	v_pk_mul_f32 v[2:3], v[2:3], v[70:71] op_sel_hi:[1,0]
	v_pk_add_f32 v[82:83], v[82:83], v[68:69] op_sel_hi:[1,0] neg_lo:[0,1] neg_hi:[0,1]
	v_pk_add_f32 v[100:101], v[100:101], v[68:69] op_sel_hi:[1,0] neg_lo:[0,1] neg_hi:[0,1]
	v_pk_add_f32 v[84:85], v[84:85], v[68:69] op_sel_hi:[1,0] neg_lo:[0,1] neg_hi:[0,1]
	v_pk_add_f32 v[102:103], v[102:103], v[68:69] op_sel_hi:[1,0] neg_lo:[0,1] neg_hi:[0,1]
	v_pk_add_f32 v[86:87], v[86:87], v[68:69] op_sel_hi:[1,0] neg_lo:[0,1] neg_hi:[0,1]
	v_pk_add_f32 v[104:105], v[104:105], v[68:69] op_sel_hi:[1,0] neg_lo:[0,1] neg_hi:[0,1]
	v_pk_add_f32 v[88:89], v[88:89], v[68:69] op_sel_hi:[1,0] neg_lo:[0,1] neg_hi:[0,1]
	v_pk_add_f32 v[106:107], v[106:107], v[68:69] op_sel_hi:[1,0] neg_lo:[0,1] neg_hi:[0,1]
	v_pk_add_f32 v[90:91], v[90:91], v[68:69] op_sel_hi:[1,0] neg_lo:[0,1] neg_hi:[0,1]
	v_pk_add_f32 v[108:109], v[108:109], v[68:69] op_sel_hi:[1,0] neg_lo:[0,1] neg_hi:[0,1]
	v_pk_add_f32 v[92:93], v[92:93], v[68:69] op_sel_hi:[1,0] neg_lo:[0,1] neg_hi:[0,1]
	v_pk_add_f32 v[110:111], v[110:111], v[68:69] op_sel_hi:[1,0] neg_lo:[0,1] neg_hi:[0,1]
	v_pk_add_f32 v[94:95], v[94:95], v[68:69] op_sel_hi:[1,0] neg_lo:[0,1] neg_hi:[0,1]
	v_pk_add_f32 v[112:113], v[112:113], v[68:69] op_sel_hi:[1,0] neg_lo:[0,1] neg_hi:[0,1]
	v_pk_add_f32 v[96:97], v[96:97], v[68:69] op_sel_hi:[1,0] neg_lo:[0,1] neg_hi:[0,1]
	v_mul_f32_e32 v0, v0, v70
	v_mov_b32_e32 v67, v66
	v_mov_b32_e32 v68, v66
	v_mov_b32_e32 v69, v66
	v_mov_b32_e32 v70, v66
	v_mov_b32_e32 v71, v66
	v_mov_b32_e32 v72, v66
	v_mov_b32_e32 v73, v66
	v_mov_b32_e32 v74, v66
	v_mov_b32_e32 v75, v66
	v_mov_b32_e32 v76, v66
	v_mov_b32_e32 v77, v66
	v_mov_b32_e32 v78, v66
	v_mov_b32_e32 v79, v66
	v_mov_b32_e32 v80, v66
	v_mov_b32_e32 v81, v66
	s_branch .LSPs_pure2
